# speedup vs baseline: 1.0006x; 1.0000x over previous
; DEV int otid() { int t = (int)threadIdx.x; asm volatile("" : "+v"(t)); return t; }
; #define PG8_STAGE(bufoff, gbase, voff) do { _Pragma("unroll") for (int _i = 0; _i < 2; ++_i) \
;         __builtin_amdgcn_global_load_lds((const unsigned*)((const char*)(gbase) + (voff)[_i]), (LAS unsigned*)(lds + (bufoff) + ldsw + _i * 8192), 16, 0, 0); } while (0)
; #define PG8_BAR __builtin_amdgcn_s_barrier()
; template <class Epi>
; DEV void gemm_phase(LAS unsigned char* lds, const Gemm g, const StaticOrder& S, const Epi& E) {
;     const int tid = otid(), wid = __builtin_amdgcn_readfirstlane(tid >> 6), lane = tid & 63, wr = wid >> 2, wc = wid & 3, fr = lane & 15, fq = lane >> 4;
;     const int K = g.K, nt = K / BK;
;     unsigned voffA[2], voffB[2];
; #pragma unroll
;     for (int i = 0; i < 2; ++i) { int R, C; stage_rc(tid * 16 + i * 8192, R, C); const int Rb = Epi::PERM ? ((R & ~31) + perm32(R & 31)) : R;
;         voffA[i] = (unsigned)(R * K + C) * 2u; voffB[i] = (unsigned)(Rb * K + C) * 2u; }
;     const size_t kstep = (size_t)(BK * 2);
;     const size_t hstep = (size_t)HALF * K * 2;
;     const size_t tstep = 2 * hstep;
;     const unsigned ldsw = (unsigned)wid * 1024u;
;     const int aoff = lds_byte(wr * 64 + fr, fq * 8), boff = lds_byte(wc * 32 + fr, fq * 8);
;     ...
;     const char* cA = (const char*)g.A + (size_t)cur.pm * tstep; const char* cB = (const char*)g.Bt + (size_t)cur.pn * tstep;
;     PG8_STAGE(PG8_SB(0, 0), cB, voffB); PG8_STAGE(PG8_SA(0, 0), cA, voffA); PG8_STAGE(PG8_SB(0, 1), cB + hstep, voffB); PG8_STAGE(PG8_SA(0, 1), cA + hstep, voffA);
;     if (wr == 1) PG8_BAR;
.LBB0_49:
	v_readlane_b32 s0, v254, 23
	s_cmpk_eq_i32 s0, 0x100
	s_cselect_b64 s[10:11], -1, 0
	s_cmpk_lg_i32 s0, 0x100
	v_cndmask_b32_e64 v0, 0, 1, s[8:9]
	s_cselect_b64 s[12:13], -1, 0
	v_cmp_ne_u32_e64 s[0:1], 1, v0
	s_andn2_b64 vcc, exec, s[8:9]
	s_cbranch_vccnz .LBB0_107
	v_ashrrev_i32_e32 v1, 31, v8
	v_lshrrev_b32_e32 v1, 26, v1
	v_add_u32_e32 v1, v8, v1
	v_ashrrev_i32_e32 v9, 6, v1
	v_bfe_i32 v1, v8, 27, 1
	v_lshlrev_b32_e32 v0, 4, v8
	v_lshrrev_b32_e32 v1, 22, v1
	v_add_u32_e32 v1, v0, v1
	v_and_b32_e32 v1, 0xfffffc00, v1
	v_sub_u32_e32 v1, v0, v1
	v_lshrrev_b32_e32 v2, 4, v1
	v_bitop3_b32 v2, v2, v1, 32 bitop3:0x6c
	v_ashrrev_i32_e32 v1, 31, v1
	v_lshrrev_b32_e32 v1, 26, v1
	v_add_u32_e32 v1, v2, v1
	v_ashrrev_i32_e32 v10, 6, v1
	v_lshlrev_b32_e32 v3, 3, v9
	v_mul_i32_i24_e32 v4, 64, v10
	v_and_b32_e32 v3, -16, v3
	v_sub_u32_e32 v2, v2, v4
	v_add_u32_e32 v1, v10, v3
	v_lshlrev_b32_e32 v3, 5, v9
	v_ashrrev_i16_sdwa v2, v203, sext(v2) dst_sel:DWORD dst_unused:UNUSED_PAD src0_sel:DWORD src1_sel:BYTE_0
	v_and_b32_e32 v3, 32, v3
	v_bfe_i32 v11, v2, 0, 16
	v_and_b32_e32 v5, 3, v10
	s_mov_b32 s5, 0xfffe0
	v_add_lshl_u32 v3, v3, v11, 1
	v_add_u32_e32 v0, 0x2000, v0
	v_lshlrev_b32_e32 v2, 1, v1
	v_lshrrev_b32_e32 v4, 2, v1
	v_and_or_b32 v5, v1, s5, v5
	v_lshl_add_u32 v144, v1, 12, v3
	v_ashrrev_i32_e32 v1, 31, v0
	v_lshrrev_b32_e32 v1, 22, v1
	v_add_u32_e32 v1, v0, v1
	v_ashrrev_i32_e32 v12, 10, v1
	v_mul_i32_i24_e32 v1, 0x400, v12
	v_sub_u32_e32 v0, v0, v1
	v_and_b32_e32 v2, 24, v2
	v_and_b32_e32 v4, 4, v4
	v_lshrrev_b32_e32 v1, 4, v0
	v_or3_b32 v2, v5, v4, v2
	v_bitop3_b32 v0, v1, v0, 32 bitop3:0x6c
	v_lshl_add_u32 v160, v2, 12, v3
	v_ashrrev_i32_e32 v2, 31, v0
	v_lshrrev_b32_e32 v2, 26, v2
	v_lshlrev_b32_e32 v1, 3, v12
	v_add_u32_e32 v2, v0, v2
	v_and_b32_e32 v1, -16, v1
	v_ashrrev_i32_e32 v13, 6, v2
	s_ashr_i32 s4, s35, 6
	v_add_u32_e32 v1, v13, v1
	v_and_b32_e32 v2, 0xc0, v2
	v_and_b32_e32 v4, 3, v13
	s_ashr_i32 s25, s24, 31
	s_ashr_i32 s15, s14, 31
	v_sub_u32_e32 v0, v0, v2
	v_and_or_b32 v4, v1, s5, v4
	s_ashr_i32 s5, s35, 8
	s_lshl_b32 s36, s4, 10
	s_lshl_b64 s[6:7], s[24:25], 20
	s_lshl_b64 s[16:17], s[14:15], 20
	v_readlane_b32 s18, v250, 35
	v_ashrrev_i16_sdwa v0, v203, sext(v0) dst_sel:DWORD dst_unused:UNUSED_PAD src0_sel:DWORD src1_sel:BYTE_0
	v_readlane_b32 s19, v250, 36
	s_add_u32 s28, s18, s16
	v_lshlrev_b32_e32 v3, 5, v12
	v_bfe_i32 v14, v0, 0, 16
	v_lshlrev_b32_e32 v0, 1, v1
	v_lshrrev_b32_e32 v2, 2, v1
	s_addc_u32 s29, s19, s17
	s_add_i32 s37, s36, 0
	v_and_b32_e32 v3, 32, v3
	v_and_b32_e32 v0, 24, v0
	v_and_b32_e32 v2, 4, v2
	s_add_i32 m0, s37, 0x10000
	v_or3_b32 v0, v4, v2, v0
	v_add_lshl_u32 v2, v3, v14, 1
	global_load_lds_dwordx4 v160, s[28:29]
	s_add_i32 m0, s37, 0x12000
	v_readlane_b32 s16, v250, 13
	v_lshl_add_u32 v148, v0, 12, v2
	v_readlane_b32 s17, v250, 14
	s_add_u32 s26, s16, s6
	global_load_lds_dwordx4 v148, s[28:29]
	s_addc_u32 s27, s17, s7
	s_mov_b32 m0, s37
	s_add_i32 s38, s37, 0x2000
	v_lshl_add_u32 v146, v1, 12, v2
	global_load_lds_dwordx4 v144, s[26:27]
	s_mov_b32 m0, s38
	s_add_u32 s6, s28, 0x80000
	global_load_lds_dwordx4 v146, s[26:27]
	s_addc_u32 s7, s29, 0
	s_add_i32 m0, s37, 0x14000
	v_mov_b32_e32 v149, v161
	global_load_lds_dwordx4 v160, s[6:7]
	s_add_i32 m0, s37, 0x16000
	v_mov_b32_e32 v145, v161
	global_load_lds_dwordx4 v148, s[6:7]
	s_add_u32 s6, s26, 0x80000
	s_addc_u32 s7, s27, 0
	s_add_i32 s39, s37, 0x4000
	s_mov_b32 m0, s39
	s_add_i32 s40, s37, 0x6000
	global_load_lds_dwordx4 v144, s[6:7]
	s_mov_b32 m0, s40
	v_mov_b32_e32 v147, v161
	global_load_lds_dwordx4 v146, s[6:7]
	v_lshl_add_u64 v[6:7], s[28:29], 0, v[160:161]
	v_lshl_add_u64 v[4:5], s[28:29], 0, v[148:149]
	v_lshl_add_u64 v[2:3], s[26:27], 0, v[144:145]
	s_cmp_lg_u32 s5, 1
	v_lshl_add_u64 v[0:1], s[26:27], 0, v[146:147]
	s_setprio 1
	s_cbranch_scc1 .LBB0_52
	s_barrier
	s_setprio 0

; DEV int otid() { int t = (int)threadIdx.x; asm volatile("" : "+v"(t)); return t; }
; #define PG8_STAGE(bufoff, gbase, voff) do { _Pragma("unroll") for (int _i = 0; _i < 2; ++_i) \
;         __builtin_amdgcn_global_load_lds((const unsigned*)((const char*)(gbase) + (voff)[_i]), (LAS unsigned*)(lds + (bufoff) + ldsw + _i * 8192), 16, 0, 0); } while (0)
; #define PG8_BAR __builtin_amdgcn_s_barrier()
; template <class Epi>
; DEV void gemm_phase(LAS unsigned char* lds, const Gemm g, const StaticOrder& S, const Epi& E) {
;     const int tid = otid(), wid = __builtin_amdgcn_readfirstlane(tid >> 6), lane = tid & 63, wr = wid >> 2, wc = wid & 3, fr = lane & 15, fq = lane >> 4;
;     const int K = g.K, nt = K / BK;
;     unsigned voffA[2], voffB[2];
; #pragma unroll
;     for (int i = 0; i < 2; ++i) { int R, C; stage_rc(tid * 16 + i * 8192, R, C); const int Rb = Epi::PERM ? ((R & ~31) + perm32(R & 31)) : R;
;         voffA[i] = (unsigned)(R * K + C) * 2u; voffB[i] = (unsigned)(Rb * K + C) * 2u; }
;     const size_t kstep = (size_t)(BK * 2);
;     const size_t hstep = (size_t)HALF * K * 2;
;     const size_t tstep = 2 * hstep;
;     const unsigned ldsw = (unsigned)wid * 1024u;
;     const int aoff = lds_byte(wr * 64 + fr, fq * 8), boff = lds_byte(wc * 32 + fr, fq * 8);
;     ...
;     const char* cA = (const char*)g.A + (size_t)cur.pm * tstep; const char* cB = (const char*)g.Bt + (size_t)cur.pn * tstep;
;     PG8_STAGE(PG8_SB(0, 0), cB, voffB); PG8_STAGE(PG8_SA(0, 0), cA, voffA); PG8_STAGE(PG8_SB(0, 1), cB + hstep, voffB); PG8_STAGE(PG8_SA(0, 1), cA + hstep, voffA);
;     if (wr == 1) PG8_BAR;
.LBB0_144:
	s_andn2_b64 vcc, exec, s[0:1]
	s_cbranch_vccnz .LBB0_212
	s_waitcnt lgkmcnt(0)
	v_ashrrev_i32_e32 v1, 31, v8
	v_lshrrev_b32_e32 v1, 26, v1
	v_add_u32_e32 v1, v8, v1
	v_ashrrev_i32_e32 v9, 6, v1
	v_bfe_i32 v1, v8, 27, 1
	v_lshlrev_b32_e32 v0, 4, v8
	v_lshrrev_b32_e32 v1, 22, v1
	v_add_u32_e32 v1, v0, v1
	v_and_b32_e32 v1, 0xfffffc00, v1
	v_sub_u32_e32 v1, v0, v1
	v_lshrrev_b32_e32 v2, 4, v1
	v_bitop3_b32 v2, v2, v1, 32 bitop3:0x6c
	v_ashrrev_i32_e32 v1, 31, v1
	v_lshrrev_b32_e32 v1, 26, v1
	v_add_u32_e32 v1, v2, v1
	v_ashrrev_i32_e32 v10, 6, v1
	v_mul_i32_i24_e32 v4, 64, v10
	v_sub_u32_e32 v2, v2, v4
	v_lshlrev_b32_e32 v3, 3, v9
	v_lshlrev_b32_e32 v1, 5, v9
	v_ashrrev_i16_sdwa v2, v203, sext(v2) dst_sel:DWORD dst_unused:UNUSED_PAD src0_sel:DWORD src1_sel:BYTE_0
	v_and_b32_e32 v3, 0xffff0, v3
	v_and_b32_e32 v1, 32, v1
	v_bfe_i32 v11, v2, 0, 16
	v_add_u32_e32 v1, v1, v11
	v_add_lshl_u32 v2, v10, v3, 12
	v_add_u32_e32 v0, 0x2000, v0
	v_lshl_add_u32 v160, v1, 1, v2
	v_ashrrev_i32_e32 v1, 31, v0
	v_lshrrev_b32_e32 v1, 22, v1
	v_add_u32_e32 v1, v0, v1
	v_ashrrev_i32_e32 v12, 10, v1
	v_mul_i32_i24_e32 v1, 0x400, v12
	v_sub_u32_e32 v0, v0, v1
	v_lshrrev_b32_e32 v1, 4, v0
	v_bitop3_b32 v0, v1, v0, 32 bitop3:0x6c
	v_ashrrev_i32_e32 v2, 31, v0
	v_lshrrev_b32_e32 v2, 26, v2
	s_ashr_i32 s0, s25, 6
	v_add_u32_e32 v2, v0, v2
	s_ashr_i32 s5, s4, 31
	s_ashr_i32 s17, s16, 31
	v_ashrrev_i32_e32 v13, 6, v2
	v_and_b32_e32 v2, 0xc0, v2
	s_ashr_i32 s1, s25, 8
	s_lshl_b32 s26, s0, 10
	s_lshl_b64 s[6:7], s[4:5], 20
	s_lshl_b64 s[8:9], s[16:17], 20
	v_readlane_b32 s10, v250, 49
	v_sub_u32_e32 v0, v0, v2
	v_readlane_b32 s11, v250, 50
	s_add_u32 s20, s10, s8
	v_lshlrev_b32_e32 v1, 3, v12
	v_lshlrev_b32_e32 v3, 5, v12
	v_ashrrev_i16_sdwa v0, v203, sext(v0) dst_sel:DWORD dst_unused:UNUSED_PAD src0_sel:DWORD src1_sel:BYTE_0
	s_addc_u32 s21, s11, s9
	s_add_i32 s17, s26, 0
	v_and_b32_e32 v1, 0xffff0, v1
	v_and_b32_e32 v3, 32, v3
	v_bfe_i32 v14, v0, 0, 16
	s_add_i32 m0, s17, 0x10000
	v_add_u32_e32 v0, v3, v14
	v_add_lshl_u32 v1, v13, v1, 12
	global_load_lds_dwordx4 v160, s[20:21]
	s_add_i32 m0, s17, 0x12000
	v_readlane_b32 s8, v250, 9
	v_lshl_add_u32 v144, v0, 1, v1
	v_readlane_b32 s9, v250, 10
	s_add_u32 s18, s8, s6
	global_load_lds_dwordx4 v144, s[20:21]
	s_addc_u32 s19, s9, s7
	s_mov_b32 m0, s17
	s_add_i32 s27, s17, 0x2000
	global_load_lds_dwordx4 v160, s[18:19]
	s_mov_b32 m0, s27
	s_add_u32 s6, s20, 0x80000
	global_load_lds_dwordx4 v144, s[18:19]
	s_addc_u32 s7, s21, 0
	s_add_i32 m0, s17, 0x14000
	v_mov_b32_e32 v145, v161
	global_load_lds_dwordx4 v160, s[6:7]
	s_add_i32 m0, s17, 0x16000
	v_lshl_add_u64 v[6:7], s[20:21], 0, v[160:161]
	global_load_lds_dwordx4 v144, s[6:7]
	s_add_u32 s6, s18, 0x80000
	s_addc_u32 s7, s19, 0
	s_add_i32 s28, s17, 0x4000
	s_mov_b32 m0, s28
	s_add_i32 s29, s17, 0x6000
	global_load_lds_dwordx4 v160, s[6:7]
	s_mov_b32 m0, s29
	v_lshl_add_u64 v[4:5], s[20:21], 0, v[144:145]
	global_load_lds_dwordx4 v144, s[6:7]
	v_lshl_add_u64 v[2:3], s[18:19], 0, v[160:161]
	s_cmp_lg_u32 s1, 1
	v_lshl_add_u64 v[0:1], s[18:19], 0, v[144:145]
	s_setprio 1
	s_cbranch_scc1 .LBB0_147
	s_barrier
	s_setprio 0

; DEV int otid() { int t = (int)threadIdx.x; asm volatile("" : "+v"(t)); return t; }
; #define PG8_STAGE(bufoff, gbase, voff) do { _Pragma("unroll") for (int _i = 0; _i < 2; ++_i) \
;         __builtin_amdgcn_global_load_lds((const unsigned*)((const char*)(gbase) + (voff)[_i]), (LAS unsigned*)(lds + (bufoff) + ldsw + _i * 8192), 16, 0, 0); } while (0)
; #define PG8_BAR __builtin_amdgcn_s_barrier()
; template <class Epi>
; DEV void gemm_phase(LAS unsigned char* lds, const Gemm g, const StaticOrder& S, const Epi& E) {
;     const int tid = otid(), wid = __builtin_amdgcn_readfirstlane(tid >> 6), lane = tid & 63, wr = wid >> 2, wc = wid & 3, fr = lane & 15, fq = lane >> 4;
;     const int K = g.K, nt = K / BK;
;     unsigned voffA[2], voffB[2];
; #pragma unroll
;     for (int i = 0; i < 2; ++i) { int R, C; stage_rc(tid * 16 + i * 8192, R, C); const int Rb = Epi::PERM ? ((R & ~31) + perm32(R & 31)) : R;
;         voffA[i] = (unsigned)(R * K + C) * 2u; voffB[i] = (unsigned)(Rb * K + C) * 2u; }
;     const size_t kstep = (size_t)(BK * 2);
;     const size_t hstep = (size_t)HALF * K * 2;
;     const size_t tstep = 2 * hstep;
;     const unsigned ldsw = (unsigned)wid * 1024u;
;     const int aoff = lds_byte(wr * 64 + fr, fq * 8), boff = lds_byte(wc * 32 + fr, fq * 8);
;     ...
;     const char* cA = (const char*)g.A + (size_t)cur.pm * tstep; const char* cB = (const char*)g.Bt + (size_t)cur.pn * tstep;
;     PG8_STAGE(PG8_SB(0, 0), cB, voffB); PG8_STAGE(PG8_SA(0, 0), cA, voffA); PG8_STAGE(PG8_SB(0, 1), cB + hstep, voffB); PG8_STAGE(PG8_SA(0, 1), cA + hstep, voffA);
;     if (wr == 1) PG8_BAR;
.LBB0_248:
	v_readlane_b32 s0, v254, 26
	v_readlane_b32 s1, v254, 27
	s_and_b64 s[0:1], s[0:1], exec
	s_mov_b32 s0, 0x1c0000
	s_cselect_b32 s0, s0, 0xc0000
	v_readlane_b32 s4, v254, 18
	v_readlane_b32 s5, v254, 19
	s_add_u32 s12, s4, s0
	s_addc_u32 s13, s5, 0
	v_readlane_b32 s0, v254, 23
	s_cmpk_eq_i32 s0, 0x100
	s_cselect_b64 s[14:15], -1, 0
	s_cmpk_lg_i32 s0, 0x100
	v_cndmask_b32_e64 v0, 0, 1, s[10:11]
	s_cselect_b64 s[16:17], -1, 0
	v_cmp_ne_u32_e64 s[0:1], 1, v0
	s_andn2_b64 vcc, exec, s[10:11]
	s_cbranch_vccnz .LBB0_306
	s_waitcnt lgkmcnt(0)
	v_ashrrev_i32_e32 v1, 31, v8
	v_lshrrev_b32_e32 v1, 26, v1
	v_add_u32_e32 v1, v8, v1
	v_ashrrev_i32_e32 v9, 6, v1
	v_bfe_i32 v1, v8, 27, 1
	v_lshlrev_b32_e32 v0, 4, v8
	v_lshrrev_b32_e32 v1, 22, v1
	v_add_u32_e32 v1, v0, v1
	v_and_b32_e32 v1, 0xfffffc00, v1
	v_sub_u32_e32 v1, v0, v1
	v_lshrrev_b32_e32 v2, 4, v1
	v_bitop3_b32 v2, v2, v1, 32 bitop3:0x6c
	v_ashrrev_i32_e32 v1, 31, v1
	v_lshrrev_b32_e32 v1, 26, v1
	v_add_u32_e32 v1, v2, v1
	v_ashrrev_i32_e32 v10, 6, v1
	v_lshlrev_b32_e32 v3, 3, v9
	v_mul_i32_i24_e32 v4, 64, v10
	v_readlane_b32 s4, v254, 26
	v_and_b32_e32 v3, -16, v3
	v_sub_u32_e32 v2, v2, v4
	v_readlane_b32 s5, v254, 27
	v_add_u32_e32 v1, v10, v3
	v_lshlrev_b32_e32 v3, 5, v9
	v_ashrrev_i16_sdwa v2, v203, sext(v2) dst_sel:DWORD dst_unused:UNUSED_PAD src0_sel:DWORD src1_sel:BYTE_0
	s_and_b64 s[4:5], s[4:5], exec
	v_and_b32_e32 v3, 32, v3
	v_bfe_i32 v11, v2, 0, 16
	v_and_b32_e32 v5, 3, v10
	s_mov_b32 s5, 0x3fffe0
	v_add_lshl_u32 v3, v3, v11, 1
	v_add_u32_e32 v0, 0x2000, v0
	v_lshlrev_b32_e32 v2, 1, v1
	v_lshrrev_b32_e32 v4, 2, v1
	v_and_or_b32 v5, v1, s5, v5
	v_lshl_add_u32 v144, v1, 10, v3
	v_ashrrev_i32_e32 v1, 31, v0
	v_lshrrev_b32_e32 v1, 22, v1
	v_add_u32_e32 v1, v0, v1
	v_ashrrev_i32_e32 v12, 10, v1
	v_mul_i32_i24_e32 v1, 0x400, v12
	v_sub_u32_e32 v0, v0, v1
	v_and_b32_e32 v2, 24, v2
	v_and_b32_e32 v4, 4, v4
	v_lshrrev_b32_e32 v1, 4, v0
	v_or3_b32 v2, v5, v4, v2
	v_bitop3_b32 v0, v1, v0, 32 bitop3:0x6c
	v_lshl_add_u32 v160, v2, 10, v3
	v_ashrrev_i32_e32 v2, 31, v0
	v_lshrrev_b32_e32 v2, 26, v2
	s_cselect_b32 s4, 0x200000, 0
	v_readlane_b32 s6, v250, 15
	v_lshlrev_b32_e32 v1, 3, v12
	v_add_u32_e32 v2, v0, v2
	v_readlane_b32 s7, v250, 16
	s_add_u32 s40, s6, s4
	v_and_b32_e32 v1, -16, v1
	v_ashrrev_i32_e32 v13, 6, v2
	s_addc_u32 s41, s7, 0
	s_ashr_i32 s4, s39, 6
	v_add_u32_e32 v1, v13, v1
	v_and_b32_e32 v2, 0xc0, v2
	v_and_b32_e32 v4, 3, v13
	s_ashr_i32 s29, s28, 31
	s_ashr_i32 s19, s18, 31
	v_sub_u32_e32 v0, v0, v2
	v_and_or_b32 v4, v1, s5, v4
	s_ashr_i32 s5, s39, 8
	s_lshl_b32 s42, s4, 10
	s_lshl_b64 s[6:7], s[28:29], 18
	s_lshl_b64 s[20:21], s[18:19], 18
	v_ashrrev_i16_sdwa v0, v203, sext(v0) dst_sel:DWORD dst_unused:UNUSED_PAD src0_sel:DWORD src1_sel:BYTE_0
	s_add_u32 s34, s40, s20
	v_lshlrev_b32_e32 v3, 5, v12
	v_bfe_i32 v14, v0, 0, 16
	v_lshlrev_b32_e32 v0, 1, v1
	v_lshrrev_b32_e32 v2, 2, v1
	s_addc_u32 s35, s41, s21
	s_add_i32 s43, s42, 0
	v_and_b32_e32 v3, 32, v3
	v_and_b32_e32 v0, 24, v0
	v_and_b32_e32 v2, 4, v2
	s_add_i32 m0, s43, 0x10000
	v_or3_b32 v0, v4, v2, v0
	v_add_lshl_u32 v2, v3, v14, 1
	global_load_lds_dwordx4 v160, s[34:35]
	s_add_i32 m0, s43, 0x12000
	v_readlane_b32 s20, v250, 13
	v_lshl_add_u32 v148, v0, 10, v2
	v_readlane_b32 s21, v250, 14
	s_add_u32 s30, s20, s6
	global_load_lds_dwordx4 v148, s[34:35]
	s_addc_u32 s31, s21, s7
	s_mov_b32 m0, s43
	s_add_i32 s44, s43, 0x2000
	v_lshl_add_u32 v146, v1, 10, v2
	global_load_lds_dwordx4 v144, s[30:31]
	s_mov_b32 m0, s44
	s_add_u32 s6, s34, 0x20000
	global_load_lds_dwordx4 v146, s[30:31]
	s_addc_u32 s7, s35, 0
	s_add_i32 m0, s43, 0x14000
	v_mov_b32_e32 v149, v161
	global_load_lds_dwordx4 v160, s[6:7]
	s_add_i32 m0, s43, 0x16000
	v_mov_b32_e32 v145, v161
	global_load_lds_dwordx4 v148, s[6:7]
	s_add_u32 s6, s30, 0x20000
	s_addc_u32 s7, s31, 0
	s_add_i32 s45, s43, 0x4000
	s_mov_b32 m0, s45
	s_add_i32 s46, s43, 0x6000
	global_load_lds_dwordx4 v144, s[6:7]
	s_mov_b32 m0, s46
	v_mov_b32_e32 v147, v161
	global_load_lds_dwordx4 v146, s[6:7]
	v_lshl_add_u64 v[6:7], s[34:35], 0, v[160:161]
	v_lshl_add_u64 v[4:5], s[34:35], 0, v[148:149]
	v_lshl_add_u64 v[2:3], s[30:31], 0, v[144:145]
	s_cmp_lg_u32 s5, 1
	v_lshl_add_u64 v[0:1], s[30:31], 0, v[146:147]
	s_setprio 1
	s_cbranch_scc1 .LBB0_251
	s_barrier
	s_setprio 0

; DEV int otid() { int t = (int)threadIdx.x; asm volatile("" : "+v"(t)); return t; }
; #define PG8_STAGE(bufoff, gbase, voff) do { _Pragma("unroll") for (int _i = 0; _i < 2; ++_i) \
;         __builtin_amdgcn_global_load_lds((const unsigned*)((const char*)(gbase) + (voff)[_i]), (LAS unsigned*)(lds + (bufoff) + ldsw + _i * 8192), 16, 0, 0); } while (0)
; #define PG8_BAR __builtin_amdgcn_s_barrier()
; template <class Epi>
; DEV void gemm_phase(LAS unsigned char* lds, const Gemm g, const StaticOrder& S, const Epi& E) {
;     const int tid = otid(), wid = __builtin_amdgcn_readfirstlane(tid >> 6), lane = tid & 63, wr = wid >> 2, wc = wid & 3, fr = lane & 15, fq = lane >> 4;
;     const int K = g.K, nt = K / BK;
;     unsigned voffA[2], voffB[2];
; #pragma unroll
;     for (int i = 0; i < 2; ++i) { int R, C; stage_rc(tid * 16 + i * 8192, R, C); const int Rb = Epi::PERM ? ((R & ~31) + perm32(R & 31)) : R;
;         voffA[i] = (unsigned)(R * K + C) * 2u; voffB[i] = (unsigned)(Rb * K + C) * 2u; }
;     const size_t kstep = (size_t)(BK * 2);
;     const size_t hstep = (size_t)HALF * K * 2;
;     const size_t tstep = 2 * hstep;
;     const unsigned ldsw = (unsigned)wid * 1024u;
;     const int aoff = lds_byte(wr * 64 + fr, fq * 8), boff = lds_byte(wc * 32 + fr, fq * 8);
;     ...
;     const char* cA = (const char*)g.A + (size_t)cur.pm * tstep; const char* cB = (const char*)g.Bt + (size_t)cur.pn * tstep;
;     PG8_STAGE(PG8_SB(0, 0), cB, voffB); PG8_STAGE(PG8_SA(0, 0), cA, voffA); PG8_STAGE(PG8_SB(0, 1), cB + hstep, voffB); PG8_STAGE(PG8_SA(0, 1), cA + hstep, voffA);
;     if (wr == 1) PG8_BAR;
.LBB0_334:
	s_waitcnt lgkmcnt(0)
	v_ashrrev_i32_e32 v1, 31, v14
	v_lshrrev_b32_e32 v1, 26, v1
	v_add_u32_e32 v1, v14, v1
	v_ashrrev_i32_e32 v8, 6, v1
	v_bfe_i32 v1, v14, 27, 1
	v_lshlrev_b32_e32 v0, 4, v14
	v_lshrrev_b32_e32 v1, 22, v1
	v_add_u32_e32 v1, v0, v1
	v_and_b32_e32 v1, 0xfffffc00, v1
	v_sub_u32_e32 v1, v0, v1
	v_lshrrev_b32_e32 v2, 4, v1
	v_bitop3_b32 v2, v2, v1, 32 bitop3:0x6c
	v_ashrrev_i32_e32 v1, 31, v1
	v_readlane_b32 s0, v254, 26
	v_lshrrev_b32_e32 v1, 26, v1
	s_ashr_i32 s5, s5, 3
	v_readlane_b32 s1, v254, 27
	v_add_u32_e32 v1, v2, v1
	s_and_b64 s[0:1], s[0:1], exec
	v_ashrrev_i32_e32 v9, 6, v1
	s_cselect_b32 s0, 0x200000, 0
	v_readlane_b32 s6, v250, 19
	v_mul_i32_i24_e32 v4, 64, v9
	v_readlane_b32 s7, v250, 20
	s_add_u32 s27, s6, s0
	v_sub_u32_e32 v2, v2, v4
	s_addc_u32 s28, s7, 0
	v_lshlrev_b32_e32 v3, 3, v8
	v_lshlrev_b32_e32 v1, 5, v8
	v_ashrrev_i16_sdwa v2, v203, sext(v2) dst_sel:DWORD dst_unused:UNUSED_PAD src0_sel:DWORD src1_sel:BYTE_0
	s_add_i32 s0, s4, s5
	v_and_b32_e32 v3, 0xffff0, v3
	v_and_b32_e32 v1, 32, v1
	v_bfe_i32 v10, v2, 0, 16
	s_ashr_i32 s1, s0, 31
	v_add_u32_e32 v1, v1, v10
	v_add_lshl_u32 v2, v9, v3, 12
	v_add_u32_e32 v0, 0x2000, v0
	s_lshr_b32 s1, s1, 28
	v_lshl_add_u32 v160, v1, 1, v2
	v_ashrrev_i32_e32 v1, 31, v0
	s_add_i32 s1, s0, s1
	v_lshrrev_b32_e32 v1, 22, v1
	s_ashr_i32 s4, s1, 4
	s_and_b32 s1, s1, -16
	v_add_u32_e32 v1, v0, v1
	s_sub_i32 s0, s0, s1
	v_ashrrev_i32_e32 v11, 10, v1
	s_bfe_i32 s1, s0, 0x80000
	v_mul_i32_i24_e32 v1, 0x400, v11
	s_bfe_u32 s1, s1, 0x3000c
	v_sub_u32_e32 v0, v0, v1
	s_add_i32 s1, s0, s1
	v_lshrrev_b32_e32 v1, 4, v0
	s_lshl_b32 s5, s4, 3
	s_bfe_i32 s4, s1, 0x80000
	s_and_b32 s1, s1, 0xf8
	v_bitop3_b32 v0, v1, v0, 32 bitop3:0x6c
	s_sub_i32 s0, s0, s1
	v_ashrrev_i32_e32 v2, 31, v0
	s_sext_i32_i16 s4, s4
	s_sext_i32_i8 s0, s0
	v_lshrrev_b32_e32 v2, 26, v2
	s_lshr_b32 s4, s4, 3
	s_add_i32 s0, s5, s0
	v_add_u32_e32 v2, v0, v2
	s_ashr_i32 s7, s25, 6
	s_ashr_i32 s1, s0, 31
	s_bfe_i64 s[12:13], s[4:5], 0x100000
	s_ashr_i32 s6, s25, 8
	v_ashrrev_i32_e32 v12, 6, v2
	v_and_b32_e32 v2, 0xc0, v2
	s_lshl_b32 s29, s7, 10
	s_lshl_b64 s[10:11], s[0:1], 20
	s_lshl_b64 s[12:13], s[12:13], 20
	v_sub_u32_e32 v0, v0, v2
	s_add_u32 s20, s27, s12
	v_lshlrev_b32_e32 v1, 3, v11
	v_lshlrev_b32_e32 v3, 5, v11
	v_ashrrev_i16_sdwa v0, v203, sext(v0) dst_sel:DWORD dst_unused:UNUSED_PAD src0_sel:DWORD src1_sel:BYTE_0
	s_addc_u32 s21, s28, s13
	s_add_i32 s30, s29, 0
	v_and_b32_e32 v1, 0xffff0, v1
	v_and_b32_e32 v3, 32, v3
	v_bfe_i32 v13, v0, 0, 16
	s_add_i32 m0, s30, 0x10000
	v_add_u32_e32 v0, v3, v13
	v_add_lshl_u32 v1, v12, v1, 12
	global_load_lds_dwordx4 v160, s[20:21]
	s_add_i32 m0, s30, 0x12000
	v_readlane_b32 s12, v250, 9
	v_lshl_add_u32 v136, v0, 1, v1
	v_readlane_b32 s13, v250, 10
	s_add_u32 s18, s12, s10
	global_load_lds_dwordx4 v136, s[20:21]
	s_addc_u32 s19, s13, s11
	s_mov_b32 m0, s30
	s_add_i32 s31, s30, 0x2000
	global_load_lds_dwordx4 v160, s[18:19]
	s_mov_b32 m0, s31
	s_add_u32 s10, s20, 0x80000
	global_load_lds_dwordx4 v136, s[18:19]
	s_addc_u32 s11, s21, 0
	s_add_i32 m0, s30, 0x14000
	v_mov_b32_e32 v137, v161
	global_load_lds_dwordx4 v160, s[10:11]
	s_add_i32 m0, s30, 0x16000
	v_lshl_add_u64 v[6:7], s[20:21], 0, v[160:161]
	global_load_lds_dwordx4 v136, s[10:11]
	s_add_u32 s10, s18, 0x80000
	s_addc_u32 s11, s19, 0
	s_add_i32 s34, s30, 0x4000
	s_mov_b32 m0, s34
	s_add_i32 s35, s30, 0x6000
	global_load_lds_dwordx4 v160, s[10:11]
	s_mov_b32 m0, s35
	v_lshl_add_u64 v[4:5], s[20:21], 0, v[136:137]
	global_load_lds_dwordx4 v136, s[10:11]
	v_lshl_add_u64 v[2:3], s[18:19], 0, v[160:161]
	s_cmp_lg_u32 s6, 1
	v_lshl_add_u64 v[0:1], s[18:19], 0, v[136:137]
	s_setprio 1
	s_cbranch_scc1 .LBB0_336
	s_barrier
	s_setprio 0

; DEV int otid() { int t = (int)threadIdx.x; asm volatile("" : "+v"(t)); return t; }
; #define PG8_STAGE(bufoff, gbase, voff) do { _Pragma("unroll") for (int _i = 0; _i < 2; ++_i) \
;         __builtin_amdgcn_global_load_lds((const unsigned*)((const char*)(gbase) + (voff)[_i]), (LAS unsigned*)(lds + (bufoff) + ldsw + _i * 8192), 16, 0, 0); } while (0)
; #define PG8_BAR __builtin_amdgcn_s_barrier()
; template <class Epi>
; DEV void gemm_phase(LAS unsigned char* lds, const Gemm g, const StaticOrder& S, const Epi& E) {
;     const int tid = otid(), wid = __builtin_amdgcn_readfirstlane(tid >> 6), lane = tid & 63, wr = wid >> 2, wc = wid & 3, fr = lane & 15, fq = lane >> 4;
;     const int K = g.K, nt = K / BK;
;     unsigned voffA[2], voffB[2];
; #pragma unroll
;     for (int i = 0; i < 2; ++i) { int R, C; stage_rc(tid * 16 + i * 8192, R, C); const int Rb = Epi::PERM ? ((R & ~31) + perm32(R & 31)) : R;
;         voffA[i] = (unsigned)(R * K + C) * 2u; voffB[i] = (unsigned)(Rb * K + C) * 2u; }
;     const size_t kstep = (size_t)(BK * 2);
;     const size_t hstep = (size_t)HALF * K * 2;
;     const size_t tstep = 2 * hstep;
;     const unsigned ldsw = (unsigned)wid * 1024u;
;     const int aoff = lds_byte(wr * 64 + fr, fq * 8), boff = lds_byte(wc * 32 + fr, fq * 8);
;     ...
;     Unit cur, nxt; int ui = 0;
;     if (!S.next(0, cur)) return;
;     f32x4 acc[2][2][4][2];
; #pragma unroll
;     for (int a = 0; a < 2; ++a)
; #pragma unroll
;         for (int b = 0; b < 2; ++b)
; #pragma unroll
;             for (int m = 0; m < 4; ++m)
; #pragma unroll
;                 for (int n = 0; n < 2; ++n) acc[a][b][m][n] = (f32x4){0.f, 0.f, 0.f, 0.f};
;     bf16x8 At[4][2], B0[2][2], B1[2][2];
;     const char* cA = (const char*)g.A + (size_t)cur.pm * tstep; const char* cB = (const char*)g.Bt + (size_t)cur.pn * tstep;
;     PG8_STAGE(PG8_SB(0, 0), cB, voffB); PG8_STAGE(PG8_SA(0, 0), cA, voffA); PG8_STAGE(PG8_SB(0, 1), cB + hstep, voffB); PG8_STAGE(PG8_SA(0, 1), cA + hstep, voffA);
;     if (wr == 1) PG8_BAR;
; DEV void run_phase(const P& p, int ph, LAS unsigned char* lds) {
;     ...
;                 const int first = (64 + 4 * l) % G;
;                 run_gemm(lds, (const u16*)(ws + O_MEMN) + (size_t)l * 256 * 2048, (const u16*)(ws + O_WXKV) + (size_t)l * 1024 * 2048, 256, 1024, 2048, E, (bx + G - first) % G); }
.LBB0_355:
	s_lshl_b32 s10, s72, 2
	s_or_b32 s10, s10, 64
	s_mul_hi_u32 s11, s10, s4
	s_mul_i32 s11, s11, s30
	s_sub_i32 s10, s10, s11
	s_sub_i32 s11, s10, s30
	s_cmp_ge_u32 s10, s30
	s_cselect_b32 s10, s11, s10
	s_sub_i32 s11, s10, s30
	s_cmp_ge_u32 s10, s30
	s_cselect_b32 s10, s11, s10
	s_sub_i32 s10, s31, s10
	s_ashr_i32 s11, s10, 31
	s_abs_i32 s10, s10
	s_mul_hi_u32 s12, s10, s4
	s_mul_i32 s12, s12, s30
	s_sub_i32 s10, s10, s12
	s_sub_i32 s12, s10, s30
	s_cmp_ge_u32 s10, s30
	s_cselect_b32 s10, s12, s10
	s_sub_i32 s12, s10, s30
	s_cmp_ge_u32 s10, s30
	s_cselect_b32 s10, s12, s10
	s_xor_b32 s10, s10, s11
	s_sub_i32 s34, s10, s11
	v_readlane_b32 s10, v250, 1
	s_mov_b32 s35, s10
	v_mov_b32_e32 v14, v198
	s_cmp_gt_i32 s34, 3
	v_readfirstlane_b32 s36, v14
	v_readlane_b32 s11, v250, 2
	s_cbranch_scc1 .LBB0_354
	v_lshlrev_b32_e32 v0, 4, v14
	s_waitcnt lgkmcnt(0)
	v_add_u32_e32 v1, 0x2000, v0
	v_ashrrev_i32_e32 v2, 31, v1
	v_lshrrev_b32_e32 v2, 22, v2
	v_add_u32_e32 v2, v1, v2
	v_ashrrev_i32_e32 v8, 10, v2
	v_mul_i32_i24_e32 v3, 0x400, v8
	v_sub_u32_e32 v1, v1, v3
	v_lshrrev_b32_e32 v3, 4, v1
	v_bitop3_b32 v1, v3, v1, 32 bitop3:0x6c
	v_ashrrev_i32_e32 v3, 31, v1
	v_lshrrev_b32_e32 v3, 26, v3
	v_add_u32_e32 v3, v1, v3
	v_ashrrev_i32_e32 v9, 6, v3
	v_and_b32_e32 v3, 0xc0, v3
	v_sub_u32_e32 v1, v1, v3
	s_lshl_b64 s[10:11], s[72:73], 20
	v_readlane_b32 s12, v250, 21
	v_lshlrev_b32_e32 v2, 5, v8
	v_ashrrev_i16_sdwa v1, v203, sext(v1) dst_sel:DWORD dst_unused:UNUSED_PAD src0_sel:DWORD src1_sel:BYTE_0
	s_add_u32 s37, s12, s10
	v_readlane_b32 s10, v250, 22
	v_and_b32_e32 v2, 32, v2
	v_bfe_i32 v10, v1, 0, 16
	s_addc_u32 s38, s10, s11
	s_lshl_b64 s[10:11], s[72:73], 22
	v_readlane_b32 s12, v250, 23
	v_add_u32_e32 v1, v2, v10
	v_lshlrev_b32_e32 v2, 3, v8
	v_readlane_b32 s13, v250, 24
	s_add_u32 s39, s12, s10
	v_and_b32_e32 v2, 0xffff0, v2
	s_addc_u32 s40, s13, s11
	v_add_lshl_u32 v2, v9, v2, 12
	s_ashr_i32 s42, s34, 31
	v_lshl_add_u32 v128, v1, 1, v2
	v_bfe_i32 v2, v14, 27, 1
	s_lshr_b32 s10, s42, 29
	v_lshrrev_b32_e32 v2, 22, v2
	s_add_i32 s10, s34, s10
	v_add_u32_e32 v2, v0, v2
	s_ashr_i32 s11, s10, 3
	s_and_b32 s10, s10, -8
	v_and_b32_e32 v2, 0xfffffc00, v2
	s_sub_i32 s10, s34, s10
	v_sub_u32_e32 v0, v0, v2
	s_add_i32 s10, s10, s11
	v_lshrrev_b32_e32 v2, 4, v0
	s_ashr_i32 s11, s10, 31
	v_bitop3_b32 v2, v2, v0, 32 bitop3:0x6c
	v_ashrrev_i32_e32 v0, 31, v0
	s_lshr_b32 s11, s11, 27
	v_lshrrev_b32_e32 v0, 26, v0
	s_add_i32 s11, s10, s11
	v_ashrrev_i32_e32 v1, 31, v14
	v_add_u32_e32 v0, v2, v0
	s_ashr_i32 s11, s11, 5
	v_lshrrev_b32_e32 v1, 26, v1
	v_ashrrev_i32_e32 v12, 6, v0
	s_lshl_b32 s12, s11, 3
	v_add_u32_e32 v1, v14, v1
	v_mul_i32_i24_e32 v0, 64, v12
	s_sub_i32 s13, 1, s12
	s_lshl_b32 s11, s11, 5
	v_ashrrev_i32_e32 v11, 6, v1
	v_sub_u32_e32 v0, v2, v0
	s_min_u32 s13, s13, 8
	s_sub_i32 s16, s10, s11
	v_lshlrev_b32_e32 v1, 5, v11
	v_ashrrev_i16_sdwa v0, v203, sext(v0) dst_sel:DWORD dst_unused:UNUSED_PAD src0_sel:DWORD src1_sel:BYTE_0
	s_sext_i32_i8 s10, s16
	v_cvt_f32_ubyte0_e32 v3, s13
	v_and_b32_e32 v1, 32, v1
	v_bfe_i32 v13, v0, 0, 16
	v_cvt_f32_i32_e32 v2, s10
	v_rcp_iflag_f32_e32 v4, v3
	v_add_u32_e32 v0, v1, v13
	v_lshlrev_b32_e32 v1, 3, v11
	v_and_b32_e32 v1, 0xffff0, v1
	v_add_lshl_u32 v1, v12, v1, 12
	v_lshl_add_u32 v160, v0, 1, v1
	v_mul_f32_e32 v0, v2, v4
	v_trunc_f32_e32 v0, v0
	v_fma_f32 v1, -v0, v3, v2
	v_cvt_i32_f32_e32 v0, v0
	s_ashr_i32 s14, s36, 6
	s_ashr_i32 s10, s10, 30
	s_ashr_i32 s15, s36, 8
	s_lshl_b32 s41, s14, 10
	s_or_b32 s17, s10, 1
	v_cmp_ge_f32_e64 s[10:11], |v1|, v3
	s_and_b64 s[10:11], s[10:11], exec
	s_cselect_b32 s10, s17, 0
	v_readfirstlane_b32 s11, v0
	s_add_i32 s10, s11, s10
	s_mul_i32 s11, s10, s13
	s_sub_i32 s11, s16, s11
	s_sext_i32_i8 s11, s11
	s_add_i32 s12, s12, s11
	s_ashr_i32 s13, s12, 31
	s_bfe_i64 s[18:19], s[10:11], 0x80000
	s_lshl_b64 s[16:17], s[12:13], 20
	s_lshl_b64 s[18:19], s[18:19], 20
	s_add_u32 s26, s39, s18
	s_addc_u32 s27, s40, s19
	s_add_i32 s13, s41, 0
	s_add_i32 m0, s13, 0x10000
	v_mov_b32_e32 v129, v161
	global_load_lds_dwordx4 v160, s[26:27]
	s_add_i32 m0, s13, 0x12000
	s_add_u32 s24, s37, s16
	global_load_lds_dwordx4 v128, s[26:27]
	s_addc_u32 s25, s38, s17
	s_mov_b32 m0, s13
	s_add_i32 s43, s13, 0x2000
	global_load_lds_dwordx4 v160, s[24:25]
	s_mov_b32 m0, s43
	s_add_u32 s16, s26, 0x80000
	global_load_lds_dwordx4 v128, s[24:25]
	s_addc_u32 s17, s27, 0
	s_add_i32 m0, s13, 0x14000
	v_lshl_add_u64 v[6:7], s[26:27], 0, v[160:161]
	global_load_lds_dwordx4 v160, s[16:17]
	s_add_i32 m0, s13, 0x16000
	v_lshl_add_u64 v[4:5], s[26:27], 0, v[128:129]
	global_load_lds_dwordx4 v128, s[16:17]
	s_add_u32 s16, s24, 0x80000
	s_addc_u32 s17, s25, 0
	s_add_i32 s44, s13, 0x4000
	s_mov_b32 m0, s44
	s_add_i32 s45, s13, 0x6000
	global_load_lds_dwordx4 v160, s[16:17]
	s_mov_b32 m0, s45
	v_lshl_add_u64 v[2:3], s[24:25], 0, v[160:161]
	global_load_lds_dwordx4 v128, s[16:17]
	s_cmp_lg_u32 s15, 1
	v_lshl_add_u64 v[0:1], s[24:25], 0, v[128:129]
	s_setprio 1
	s_cbranch_scc1 .LBB0_358
	s_barrier
	s_setprio 0

; DEV int otid() { int t = (int)threadIdx.x; asm volatile("" : "+v"(t)); return t; }
; #define PG8_STAGE(bufoff, gbase, voff) do { _Pragma("unroll") for (int _i = 0; _i < 2; ++_i) \
;         __builtin_amdgcn_global_load_lds((const unsigned*)((const char*)(gbase) + (voff)[_i]), (LAS unsigned*)(lds + (bufoff) + ldsw + _i * 8192), 16, 0, 0); } while (0)
; #define PG8_BAR __builtin_amdgcn_s_barrier()
; template <class Epi>
; DEV void gemm_phase(LAS unsigned char* lds, const Gemm g, const StaticOrder& S, const Epi& E) {
;     const int tid = otid(), wid = __builtin_amdgcn_readfirstlane(tid >> 6), lane = tid & 63, wr = wid >> 2, wc = wid & 3, fr = lane & 15, fq = lane >> 4;
;     const int K = g.K, nt = K / BK;
;     unsigned voffA[2], voffB[2];
; #pragma unroll
;     for (int i = 0; i < 2; ++i) { int R, C; stage_rc(tid * 16 + i * 8192, R, C); const int Rb = Epi::PERM ? ((R & ~31) + perm32(R & 31)) : R;
;         voffA[i] = (unsigned)(R * K + C) * 2u; voffB[i] = (unsigned)(Rb * K + C) * 2u; }
;     const size_t kstep = (size_t)(BK * 2);
;     const size_t hstep = (size_t)HALF * K * 2;
;     const size_t tstep = 2 * hstep;
;     const unsigned ldsw = (unsigned)wid * 1024u;
;     const int aoff = lds_byte(wr * 64 + fr, fq * 8), boff = lds_byte(wc * 32 + fr, fq * 8);
;     ...
;     const char* cA = (const char*)g.A + (size_t)cur.pm * tstep; const char* cB = (const char*)g.Bt + (size_t)cur.pn * tstep;
;     PG8_STAGE(PG8_SB(0, 0), cB, voffB); PG8_STAGE(PG8_SA(0, 0), cA, voffA); PG8_STAGE(PG8_SB(0, 1), cB + hstep, voffB); PG8_STAGE(PG8_SA(0, 1), cA + hstep, voffA);
;     if (wr == 1) PG8_BAR;
.LBB0_392:
	v_readlane_b32 s0, v254, 23
	s_cmpk_eq_i32 s0, 0x100
	s_cselect_b64 s[10:11], -1, 0
	s_cmpk_lg_i32 s0, 0x100
	v_cndmask_b32_e64 v0, 0, 1, s[8:9]
	s_cselect_b64 s[12:13], -1, 0
	v_cmp_ne_u32_e64 s[0:1], 1, v0
	s_andn2_b64 vcc, exec, s[8:9]
	s_cbranch_vccnz .LBB0_450
	s_waitcnt lgkmcnt(0)
	v_ashrrev_i32_e32 v1, 31, v8
	v_lshrrev_b32_e32 v1, 26, v1
	v_add_u32_e32 v1, v8, v1
	v_ashrrev_i32_e32 v9, 6, v1
	v_bfe_i32 v1, v8, 27, 1
	v_lshlrev_b32_e32 v0, 4, v8
	v_lshrrev_b32_e32 v1, 22, v1
	v_add_u32_e32 v1, v0, v1
	v_and_b32_e32 v1, 0xfffffc00, v1
	v_sub_u32_e32 v1, v0, v1
	v_lshrrev_b32_e32 v2, 4, v1
	v_bitop3_b32 v2, v2, v1, 32 bitop3:0x6c
	v_ashrrev_i32_e32 v1, 31, v1
	v_lshrrev_b32_e32 v1, 26, v1
	v_add_u32_e32 v1, v2, v1
	v_ashrrev_i32_e32 v10, 6, v1
	v_lshlrev_b32_e32 v3, 3, v9
	v_mul_i32_i24_e32 v4, 64, v10
	v_and_b32_e32 v3, -16, v3
	v_sub_u32_e32 v2, v2, v4
	v_add_u32_e32 v1, v10, v3
	v_lshlrev_b32_e32 v3, 5, v9
	v_ashrrev_i16_sdwa v2, v203, sext(v2) dst_sel:DWORD dst_unused:UNUSED_PAD src0_sel:DWORD src1_sel:BYTE_0
	v_and_b32_e32 v3, 32, v3
	v_bfe_i32 v11, v2, 0, 16
	v_and_b32_e32 v5, 3, v10
	s_mov_b32 s5, 0x7ffe0
	v_add_lshl_u32 v3, v3, v11, 1
	v_add_u32_e32 v0, 0x2000, v0
	v_lshlrev_b32_e32 v2, 1, v1
	v_lshrrev_b32_e32 v4, 2, v1
	v_and_or_b32 v5, v1, s5, v5
	v_lshl_add_u32 v144, v1, 13, v3
	v_ashrrev_i32_e32 v1, 31, v0
	v_lshrrev_b32_e32 v1, 22, v1
	v_add_u32_e32 v1, v0, v1
	v_ashrrev_i32_e32 v12, 10, v1
	v_mul_i32_i24_e32 v1, 0x400, v12
	v_sub_u32_e32 v0, v0, v1
	v_and_b32_e32 v2, 24, v2
	v_and_b32_e32 v4, 4, v4
	v_lshrrev_b32_e32 v1, 4, v0
	v_or3_b32 v2, v5, v4, v2
	v_bitop3_b32 v0, v1, v0, 32 bitop3:0x6c
	v_lshl_add_u32 v160, v2, 13, v3
	v_ashrrev_i32_e32 v2, 31, v0
	v_lshrrev_b32_e32 v2, 26, v2
	v_lshlrev_b32_e32 v1, 3, v12
	v_add_u32_e32 v2, v0, v2
	v_and_b32_e32 v1, -16, v1
	v_ashrrev_i32_e32 v13, 6, v2
	s_ashr_i32 s4, s35, 6
	v_add_u32_e32 v1, v13, v1
	v_and_b32_e32 v2, 0xc0, v2
	v_and_b32_e32 v4, 3, v13
	s_ashr_i32 s25, s24, 31
	s_ashr_i32 s15, s14, 31
	v_sub_u32_e32 v0, v0, v2
	v_and_or_b32 v4, v1, s5, v4
	s_ashr_i32 s5, s35, 8
	s_lshl_b32 s36, s4, 10
	s_lshl_b64 s[6:7], s[24:25], 21
	s_lshl_b64 s[16:17], s[14:15], 21
	v_readlane_b32 s18, v250, 57
	v_ashrrev_i16_sdwa v0, v203, sext(v0) dst_sel:DWORD dst_unused:UNUSED_PAD src0_sel:DWORD src1_sel:BYTE_0
	v_readlane_b32 s19, v250, 58
	s_add_u32 s28, s18, s16
	v_lshlrev_b32_e32 v3, 5, v12
	v_bfe_i32 v14, v0, 0, 16
	v_lshlrev_b32_e32 v0, 1, v1
	v_lshrrev_b32_e32 v2, 2, v1
	s_addc_u32 s29, s19, s17
	s_add_i32 s37, s36, 0
	v_and_b32_e32 v3, 32, v3
	v_and_b32_e32 v0, 24, v0
	v_and_b32_e32 v2, 4, v2
	s_add_i32 m0, s37, 0x10000
	v_or3_b32 v0, v4, v2, v0
	v_add_lshl_u32 v2, v3, v14, 1
	global_load_lds_dwordx4 v160, s[28:29]
	s_add_i32 m0, s37, 0x12000
	v_readlane_b32 s16, v250, 13
	v_lshl_add_u32 v148, v0, 13, v2
	v_readlane_b32 s17, v250, 14
	s_add_u32 s26, s16, s6
	global_load_lds_dwordx4 v148, s[28:29]
	s_addc_u32 s27, s17, s7
	s_mov_b32 m0, s37
	s_add_i32 s38, s37, 0x2000
	v_lshl_add_u32 v146, v1, 13, v2
	global_load_lds_dwordx4 v144, s[26:27]
	s_mov_b32 m0, s38
	s_add_u32 s6, s28, 0x100000
	global_load_lds_dwordx4 v146, s[26:27]
	s_addc_u32 s7, s29, 0
	s_add_i32 m0, s37, 0x14000
	v_mov_b32_e32 v149, v161
	global_load_lds_dwordx4 v160, s[6:7]
	s_add_i32 m0, s37, 0x16000
	v_mov_b32_e32 v145, v161
	global_load_lds_dwordx4 v148, s[6:7]
	s_add_u32 s6, s26, 0x100000
	s_addc_u32 s7, s27, 0
	s_add_i32 s39, s37, 0x4000
	s_mov_b32 m0, s39
	s_add_i32 s40, s37, 0x6000
	global_load_lds_dwordx4 v144, s[6:7]
	s_mov_b32 m0, s40
	v_mov_b32_e32 v147, v161
	global_load_lds_dwordx4 v146, s[6:7]
	v_lshl_add_u64 v[6:7], s[28:29], 0, v[160:161]
	v_lshl_add_u64 v[4:5], s[28:29], 0, v[148:149]
	v_lshl_add_u64 v[2:3], s[26:27], 0, v[144:145]
	s_cmp_lg_u32 s5, 1
	v_lshl_add_u64 v[0:1], s[26:27], 0, v[146:147]
	s_setprio 1
	s_cbranch_scc1 .LBB0_395
	s_barrier
	s_setprio 0

; #define LAS __attribute__((address_space(3)))
; DEV int otid() { int t = (int)threadIdx.x; asm volatile("" : "+v"(t)); return t; }
; #define PG8_STAGE(bufoff, gbase, voff) do { _Pragma("unroll") for (int _i = 0; _i < 2; ++_i) \
;         __builtin_amdgcn_global_load_lds((const unsigned*)((const char*)(gbase) + (voff)[_i]), (LAS unsigned*)(lds + (bufoff) + ldsw + _i * 8192), 16, 0, 0); } while (0)
; #define PG8_BAR __builtin_amdgcn_s_barrier()
;     DEV bool next(int i, Unit& u) const {
;         const long L = (long)i * G + c; if (L >= nwg) return false;
;         int wgid = (int)L; { const int q = nwg / NXCD, r = nwg % NXCD, xcd = wgid % NXCD, off = wgid / NXCD; wgid = (xcd < r ? xcd * (q + 1) : r * (q + 1) + (xcd - r) * q) + off; }
;         const int nig = WGM * nN, gid = wgid / nig, fm = gid * WGM, gsz = (nM - fm) < WGM ? (nM - fm) : WGM;
;         u.pm = fm + ((wgid % nig) % gsz); u.pn = (wgid % nig) / gsz; return true;
;     }
; template <class Epi>
; DEV void gemm_phase(LAS unsigned char* lds, const Gemm g, const StaticOrder& S, const Epi& E) {
;     const int tid = otid(), wid = __builtin_amdgcn_readfirstlane(tid >> 6), lane = tid & 63, wr = wid >> 2, wc = wid & 3, fr = lane & 15, fq = lane >> 4;
;     const int K = g.K, nt = K / BK;
;     unsigned voffA[2], voffB[2];
; #pragma unroll
;     for (int i = 0; i < 2; ++i) { int R, C; stage_rc(tid * 16 + i * 8192, R, C); const int Rb = Epi::PERM ? ((R & ~31) + perm32(R & 31)) : R;
;         voffA[i] = (unsigned)(R * K + C) * 2u; voffB[i] = (unsigned)(Rb * K + C) * 2u; }
;     const size_t kstep = (size_t)(BK * 2);
;     const size_t hstep = (size_t)HALF * K * 2;
;     const size_t tstep = 2 * hstep;
;     const unsigned ldsw = (unsigned)wid * 1024u;
;     const int aoff = lds_byte(wr * 64 + fr, fq * 8), boff = lds_byte(wc * 32 + fr, fq * 8);
;     ...
;     const char* cA = (const char*)g.A + (size_t)cur.pm * tstep; const char* cB = (const char*)g.Bt + (size_t)cur.pn * tstep;
;     PG8_STAGE(PG8_SB(0, 0), cB, voffB); PG8_STAGE(PG8_SA(0, 0), cA, voffA); PG8_STAGE(PG8_SB(0, 1), cB + hstep, voffB); PG8_STAGE(PG8_SA(0, 1), cA + hstep, voffA);
;     if (wr == 1) PG8_BAR;
.LBB0_579:
	s_andn2_b64 vcc, exec, s[0:1]
	s_cbranch_vccnz .LBB0_630
	v_readlane_b32 s0, v250, 1
	s_mov_b32 s20, s0
	v_mov_b32_e32 v10, v198
	v_readlane_b32 s7, v254, 20
	s_cmpk_gt_i32 s7, 0x49f
	v_readfirstlane_b32 s21, v10
	v_readlane_b32 s1, v250, 2
	s_cbranch_scc1 .LBB0_606
	v_lshlrev_b32_e32 v0, 4, v10
	s_waitcnt lgkmcnt(0)
	v_add_u32_e32 v1, 0x2000, v0
	v_ashrrev_i32_e32 v2, 31, v1
	v_lshrrev_b32_e32 v2, 22, v2
	v_add_u32_e32 v2, v1, v2
	v_ashrrev_i32_e32 v8, 10, v2
	v_mul_i32_i24_e32 v2, 0x400, v8
	v_sub_u32_e32 v1, v1, v2
	v_lshrrev_b32_e32 v2, 4, v1
	v_bitop3_b32 v1, v2, v1, 32 bitop3:0x6c
	v_ashrrev_i32_e32 v2, 31, v1
	v_lshrrev_b32_e32 v2, 26, v2
	v_add_u32_e32 v2, v1, v2
	v_lshlrev_b32_e32 v3, 3, v8
	v_ashrrev_i32_e32 v9, 6, v2
	v_and_b32_e32 v3, -16, v3
	v_add_u32_e32 v3, v9, v3
	v_and_b32_e32 v4, 3, v9
	s_mov_b32 s0, 0xfffe0
	v_lshrrev_b32_e32 v5, 2, v3
	v_lshlrev_b32_e32 v6, 1, v3
	v_and_b32_e32 v2, 0xc0, v2
	v_and_or_b32 v4, v3, s0, v4
	v_and_b32_e32 v5, 4, v5
	v_and_b32_e32 v6, 24, v6
	v_sub_u32_e32 v1, v1, v2
	v_or3_b32 v4, v4, v5, v6
	v_lshlrev_b32_e32 v5, 5, v8
	v_ashrrev_i16_sdwa v1, v203, sext(v1) dst_sel:DWORD dst_unused:UNUSED_PAD src0_sel:DWORD src1_sel:BYTE_0
	v_and_b32_e32 v5, 32, v5
	v_bfe_i32 v11, v1, 0, 16
	v_add_lshl_u32 v1, v5, v11, 1
	v_lshl_add_u32 v136, v4, 12, v1
	v_lshl_add_u32 v138, v3, 12, v1
	v_bfe_i32 v1, v10, 27, 1
	v_lshrrev_b32_e32 v1, 22, v1
	v_add_u32_e32 v1, v0, v1
	v_and_b32_e32 v1, 0xfffffc00, v1
	v_sub_u32_e32 v0, v0, v1
	v_lshrrev_b32_e32 v1, 4, v0
	v_bitop3_b32 v1, v1, v0, 32 bitop3:0x6c
	v_ashrrev_i32_e32 v0, 31, v0
	v_lshrrev_b32_e32 v0, 26, v0
	v_add_u32_e32 v0, v1, v0
	v_ashrrev_i32_e32 v12, 6, v0
	v_ashrrev_i32_e32 v0, 31, v10
	v_lshrrev_b32_e32 v0, 26, v0
	v_add_u32_e32 v0, v10, v0
	v_ashrrev_i32_e32 v13, 6, v0
	v_lshlrev_b32_e32 v0, 3, v13
	v_and_b32_e32 v0, -16, v0
	v_add_u32_e32 v0, v12, v0
	v_and_b32_e32 v2, 3, v12
	s_ashr_i32 s23, s7, 31
	v_and_or_b32 v2, v0, s0, v2
	s_lshr_b32 s0, s23, 29
	s_add_i32 s0, s7, s0
	s_ashr_i32 s6, s21, 6
	s_ashr_i32 s1, s0, 3
	s_and_b32 s0, s0, -8
	s_ashr_i32 s5, s21, 8
	s_lshl_b32 s22, s6, 10
	s_sub_i32 s0, s7, s0
	s_cmp_lt_i32 s0, 0
	s_movk_i32 s4, 0x95
	s_cselect_b32 s4, s4, 0x94
	s_mul_i32 s0, s4, s0
	s_add_i32 s0, s0, s1
	s_mul_hi_i32 s1, s0, 0xdd67c8a7
	s_add_i32 s1, s1, s0
	s_lshr_b32 s4, s1, 31
	s_ashr_i32 s1, s1, 8
	s_add_i32 s1, s1, s4
	s_lshl_b32 s7, s1, 3
	s_mulk_i32 s1, 0x128
	s_sub_i32 s0, s0, s1
	s_sext_i32_i16 s1, s0
	s_bfe_u32 s1, s1, 0x3001c
	s_add_i32 s1, s0, s1
	s_sext_i32_i16 s4, s1
	s_and_b32 s1, s1, 0xfff8
	v_lshrrev_b32_e32 v3, 2, v0
	v_lshlrev_b32_e32 v4, 1, v0
	s_sub_i32 s0, s0, s1
	v_and_b32_e32 v3, 4, v3
	v_and_b32_e32 v4, 24, v4
	s_sext_i32_i16 s0, s0
	v_or3_b32 v2, v2, v3, v4
	v_mul_i32_i24_e32 v4, 64, v12
	s_lshr_b32 s4, s4, 3
	s_add_i32 s0, s7, s0
	v_sub_u32_e32 v1, v1, v4
	s_ashr_i32 s1, s0, 31
	s_bfe_i64 s[10:11], s[4:5], 0x100000
	v_lshlrev_b32_e32 v3, 5, v13
	v_ashrrev_i16_sdwa v1, v203, sext(v1) dst_sel:DWORD dst_unused:UNUSED_PAD src0_sel:DWORD src1_sel:BYTE_0
	s_lshl_b64 s[8:9], s[0:1], 20
	s_lshl_b64 s[10:11], s[10:11], 20
	v_readlane_b32 s12, v251, 41
	v_and_b32_e32 v3, 32, v3
	v_bfe_i32 v14, v1, 0, 16
	v_readlane_b32 s13, v251, 42
	s_add_u32 s16, s12, s10
	v_add_lshl_u32 v1, v3, v14, 1
	s_addc_u32 s17, s13, s11
	s_add_i32 s24, s22, 0
	v_lshl_add_u32 v140, v2, 12, v1
	s_add_i32 m0, s24, 0x10000
	v_readlane_b32 s10, v250, 9
	global_load_lds_dwordx4 v140, s[16:17]
	s_add_i32 m0, s24, 0x12000
	v_readlane_b32 s11, v250, 10
	s_add_u32 s14, s10, s8
	v_lshl_add_u32 v142, v0, 12, v1
	global_load_lds_dwordx4 v136, s[16:17]
	s_addc_u32 s15, s11, s9
	s_mov_b32 m0, s24
	s_add_i32 s25, s24, 0x2000
	global_load_lds_dwordx4 v142, s[14:15]
	s_mov_b32 m0, s25
	s_add_u32 s8, s16, 0x80000
	global_load_lds_dwordx4 v138, s[14:15]
	s_addc_u32 s9, s17, 0
	s_add_i32 m0, s24, 0x14000
	v_mov_b32_e32 v141, v161
	global_load_lds_dwordx4 v140, s[8:9]
	s_add_i32 m0, s24, 0x16000
	v_mov_b32_e32 v137, v161
	global_load_lds_dwordx4 v136, s[8:9]
	s_add_u32 s8, s14, 0x80000
	s_addc_u32 s9, s15, 0
	s_add_i32 s26, s24, 0x4000
	s_mov_b32 m0, s26
	s_add_i32 s27, s24, 0x6000
	global_load_lds_dwordx4 v142, s[8:9]
	s_mov_b32 m0, s27
	v_mov_b32_e32 v143, v161
	global_load_lds_dwordx4 v138, s[8:9]
	v_mov_b32_e32 v139, v161
	v_lshl_add_u64 v[6:7], s[16:17], 0, v[140:141]
	v_lshl_add_u64 v[4:5], s[16:17], 0, v[136:137]
	v_lshl_add_u64 v[2:3], s[14:15], 0, v[142:143]
	s_cmp_lg_u32 s5, 1
	v_lshl_add_u64 v[0:1], s[14:15], 0, v[138:139]
	s_setprio 1
	s_cbranch_scc1 .LBB0_583
	s_barrier
	s_setprio 0

; DEV int otid() { int t = (int)threadIdx.x; asm volatile("" : "+v"(t)); return t; }
; #define PG8_BAR __builtin_amdgcn_s_barrier()
; template <class Epi>
; DEV void gemm_phase(LAS unsigned char* lds, const Gemm g, const StaticOrder& S, const Epi& E) {
;     const int tid = otid(), wid = __builtin_amdgcn_readfirstlane(tid >> 6), lane = tid & 63, wr = wid >> 2, wc = wid & 3, fr = lane & 15, fq = lane >> 4;
;     const int K = g.K, nt = K / BK;
;     unsigned voffA[2], voffB[2];
; #pragma unroll
;     for (int i = 0; i < 2; ++i) { int R, C; stage_rc(tid * 16 + i * 8192, R, C); const int Rb = Epi::PERM ? ((R & ~31) + perm32(R & 31)) : R;
;         voffA[i] = (unsigned)(R * K + C) * 2u; voffB[i] = (unsigned)(Rb * K + C) * 2u; }
;     const size_t kstep = (size_t)(BK * 2);
;     const size_t hstep = (size_t)HALF * K * 2;
;     const size_t tstep = 2 * hstep;
;     const unsigned ldsw = (unsigned)wid * 1024u;
;     const int aoff = lds_byte(wr * 64 + fr, fq * 8), boff = lds_byte(wc * 32 + fr, fq * 8);
;     ...
;     Unit cur, nxt; int ui = 0;
;     if (!S.next(0, cur)) return;
;     f32x4 acc[2][2][4][2];
; #pragma unroll
;     for (int a = 0; a < 2; ++a)
; #pragma unroll
;         for (int b = 0; b < 2; ++b)
; #pragma unroll
;             for (int m = 0; m < 4; ++m)
; #pragma unroll
;                 for (int n = 0; n < 2; ++n) acc[a][b][m][n] = (f32x4){0.f, 0.f, 0.f, 0.f};
;     bf16x8 At[4][2], B0[2][2], B1[2][2];
;     const char* cA = (const char*)g.A + (size_t)cur.pm * tstep; const char* cB = (const char*)g.Bt + (size_t)cur.pn * tstep;
;     PG8_STAGE(PG8_SB(0, 0), cB, voffB); PG8_STAGE(PG8_SA(0, 0), cA, voffA); PG8_STAGE(PG8_SB(0, 1), cB + hstep, voffB); PG8_STAGE(PG8_SA(0, 1), cA + hstep, voffA);
;     if (wr == 1) PG8_BAR;
; DEV void run_phase(const P& p, int ph, LAS unsigned char* lds) {
;     ...
;     case L0_DN1: case L1_DN1: case L0_DN2: case L1_DN2: {
;         const int second = (ph == L0_DN2 || ph == L1_DN2) ? 1 : 0; const int k = 2 * L + second; const bool lastp = (ph == L1_DN2);
;         run_resid_gemm(lds, ACT, (const u16*)(ws + O_WDN + k * SZ_WDN), 5632, (ph == L0_DN1) ? p.x : XW, XW, 0.5f, lastp ? nullptr : XB, lastp ? nullptr : SS + (size_t)(4 * L + (second ? 4 : 1)) * 65536, bx, G);
.LBB0_641:
	v_readlane_b32 s8, v250, 7
	s_cmp_lg_u32 s8, 23
	v_readlane_b32 s0, v254, 26
	s_cselect_b64 s[18:19], -1, 0
	s_cmp_eq_u32 s8, 23
	v_readlane_b32 s1, v254, 27
	s_cselect_b64 s[6:7], -1, 0
	s_and_b64 s[0:1], s[0:1], exec
	v_readlane_b32 s9, v250, 8
	s_cselect_b32 s4, 4, 0
	s_cmp_eq_u32 s8, 13
	s_cselect_b64 s[8:9], -1, 0
	s_and_b64 s[0:1], s[8:9], exec
	s_cselect_b32 s0, 4, 1
	s_add_i32 s4, s4, s0
	s_lshl_b32 s0, s4, 18
	s_add_u32 s16, s74, s0
	s_addc_u32 s17, s75, 0
	v_readlane_b32 s0, v254, 23
	s_cmpk_lg_i32 s0, 0x100
	s_cselect_b64 s[0:1], -1, 0
	s_or_b64 s[4:5], s[6:7], s[0:1]
	v_cndmask_b32_e64 v0, 0, 1, s[14:15]
	v_cmp_ne_u32_e64 s[0:1], 1, v0
	s_andn2_b64 vcc, exec, s[14:15]
	s_xor_b64 s[20:21], s[4:5], -1
	s_cbranch_vccnz .LBB0_735
	s_or_b64 s[6:7], s[8:9], s[6:7]
	s_waitcnt lgkmcnt(0)
	v_ashrrev_i32_e32 v1, 31, v8
	v_cndmask_b32_e64 v0, 0, 1, s[6:7]
	v_readlane_b32 s6, v254, 26
	v_lshrrev_b32_e32 v1, 26, v1
	v_readlane_b32 s7, v254, 27
	v_add_u32_e32 v1, v8, v1
	s_and_b64 s[6:7], s[6:7], exec
	v_ashrrev_i32_e32 v9, 6, v1
	v_bfe_i32 v1, v8, 27, 1
	v_readfirstlane_b32 s7, v0
	v_lshlrev_b32_e32 v0, 4, v8
	v_lshrrev_b32_e32 v1, 22, v1
	v_add_u32_e32 v1, v0, v1
	v_and_b32_e32 v1, 0xfffffc00, v1
	v_sub_u32_e32 v1, v0, v1
	v_lshrrev_b32_e32 v2, 4, v1
	v_bitop3_b32 v2, v2, v1, 32 bitop3:0x6c
	v_ashrrev_i32_e32 v1, 31, v1
	v_lshrrev_b32_e32 v1, 26, v1
	v_lshlrev_b32_e32 v3, 3, v9
	v_add_u32_e32 v1, v2, v1
	v_and_b32_e32 v3, -16, v3
	v_ashrrev_i32_e32 v11, 6, v1
	s_cselect_b32 s6, 2, 0
	v_add_u32_e32 v1, v11, v3
	v_lshlrev_b32_e32 v3, 5, v9
	s_or_b32 s6, s6, s7
	v_and_b32_e32 v10, 32, v3
	v_mul_i32_i24_e32 v3, 64, v11
	s_mul_i32 s6, s6, 0x1600000
	v_readlane_b32 s8, v251, 63
	v_sub_u32_e32 v2, v2, v3
	s_add_u32 s38, s8, s6
	v_ashrrev_i16_sdwa v2, v203, sext(v2) dst_sel:DWORD dst_unused:UNUSED_PAD src0_sel:DWORD src1_sel:BYTE_0
	v_lshlrev_b32_e32 v3, 1, v1
	v_lshrrev_b32_e32 v4, 2, v1
	v_and_b32_e32 v5, 3, v11
	s_mov_b32 s8, 0x7fffe0
	v_bfe_i32 v12, v2, 0, 16
	v_and_b32_e32 v3, 24, v3
	v_and_b32_e32 v4, 4, v4
	v_and_or_b32 v5, v1, s8, v5
	s_movk_i32 s7, 0x1600
	v_add_u32_e32 v2, v10, v12
	v_or3_b32 v3, v5, v4, v3
	v_mul_lo_u32 v1, v1, s7
	v_add_lshl_u32 v174, v2, v1, 1
	v_mul_u32_u24_e32 v1, 0x1600, v3
	v_add_u32_e32 v0, 0x2000, v0
	v_add_lshl_u32 v160, v1, v2, 1
	v_ashrrev_i32_e32 v1, 31, v0
	v_lshrrev_b32_e32 v1, 22, v1
	v_add_u32_e32 v1, v0, v1
	v_ashrrev_i32_e32 v13, 10, v1
	v_mul_i32_i24_e32 v1, 0x400, v13
	v_sub_u32_e32 v0, v0, v1
	v_lshrrev_b32_e32 v1, 4, v0
	v_bitop3_b32 v0, v1, v0, 32 bitop3:0x6c
	v_ashrrev_i32_e32 v2, 31, v0
	v_lshrrev_b32_e32 v2, 26, v2
	v_lshlrev_b32_e32 v1, 3, v13
	v_add_u32_e32 v2, v0, v2
	v_readlane_b32 s9, v252, 0
	v_and_b32_e32 v1, -16, v1
	v_ashrrev_i32_e32 v15, 6, v2
	s_addc_u32 s39, s9, 0
	s_ashr_i32 s6, s37, 6
	v_add_u32_e32 v1, v15, v1
	v_lshlrev_b32_e32 v3, 5, v13
	v_and_b32_e32 v2, 0xc0, v2
	v_and_b32_e32 v4, 3, v15
	v_and_b32_e32 v14, 32, v3
	v_sub_u32_e32 v0, v0, v2
	v_lshlrev_b32_e32 v2, 1, v1
	v_lshrrev_b32_e32 v3, 2, v1
	v_and_or_b32 v4, v1, s8, v4
	v_mul_lo_u32 v1, v1, s7
	s_ashr_i32 s7, s37, 8
	s_lshl_b32 s40, s6, 10
	s_mul_i32 s11, s22, 0x2c0000
	v_ashrrev_i16_sdwa v0, v203, sext(v0) dst_sel:DWORD dst_unused:UNUSED_PAD src0_sel:DWORD src1_sel:BYTE_0
	s_mul_hi_i32 s10, s22, 0x2c0000
	s_add_u32 s30, s38, s11
	v_bfe_i32 v16, v0, 0, 16
	v_and_b32_e32 v2, 24, v2
	v_and_b32_e32 v3, 4, v3
	s_addc_u32 s31, s39, s10
	s_add_i32 s41, s40, 0
	v_add_u32_e32 v0, v14, v16
	v_or3_b32 v2, v4, v3, v2
	s_add_i32 m0, s41, 0x10000
	v_add_lshl_u32 v176, v0, v1, 1
	v_mul_u32_u24_e32 v1, 0x1600, v2
	s_mul_i32 s9, s23, 0x2c0000
	global_load_lds_dwordx4 v160, s[30:31]
	s_add_i32 m0, s41, 0x12000
	v_readlane_b32 s10, v250, 11
	v_add_lshl_u32 v178, v1, v0, 1
	s_mul_hi_i32 s8, s23, 0x2c0000
	v_readlane_b32 s11, v250, 12
	s_add_u32 s28, s10, s9
	global_load_lds_dwordx4 v178, s[30:31]
	s_addc_u32 s29, s11, s8
	s_mov_b32 m0, s41
	s_add_i32 s42, s41, 0x2000
	global_load_lds_dwordx4 v174, s[28:29]
	s_mov_b32 m0, s42
	s_add_u32 s8, s30, 0x160000
	global_load_lds_dwordx4 v176, s[28:29]
	s_addc_u32 s9, s31, 0
	s_add_i32 m0, s41, 0x14000
	v_mov_b32_e32 v179, v161
	global_load_lds_dwordx4 v160, s[8:9]
	s_add_i32 m0, s41, 0x16000
	v_mov_b32_e32 v175, v161
	global_load_lds_dwordx4 v178, s[8:9]
	s_add_u32 s8, s28, 0x160000
	s_addc_u32 s9, s29, 0
	s_add_i32 s43, s41, 0x4000
	s_mov_b32 m0, s43
	s_add_i32 s44, s41, 0x6000
	global_load_lds_dwordx4 v174, s[8:9]
	s_mov_b32 m0, s44
	v_mov_b32_e32 v177, v161
	global_load_lds_dwordx4 v176, s[8:9]
	v_lshl_add_u64 v[6:7], s[30:31], 0, v[160:161]
	v_lshl_add_u64 v[4:5], s[30:31], 0, v[178:179]
	v_lshl_add_u64 v[2:3], s[28:29], 0, v[174:175]
	s_cmp_lg_u32 s7, 1
	v_lshl_add_u64 v[0:1], s[28:29], 0, v[176:177]
	s_setprio 1
	s_cbranch_scc1 .LBB0_644
	s_barrier
	s_setprio 0

; DEV int otid() { int t = (int)threadIdx.x; asm volatile("" : "+v"(t)); return t; }
; #define PG8_BAR __builtin_amdgcn_s_barrier()
; template <class Epi>
; DEV void gemm_phase(LAS unsigned char* lds, const Gemm g, const StaticOrder& S, const Epi& E) {
;     const int tid = otid(), wid = __builtin_amdgcn_readfirstlane(tid >> 6), lane = tid & 63, wr = wid >> 2, wc = wid & 3, fr = lane & 15, fq = lane >> 4;
;     const int K = g.K, nt = K / BK;
;     unsigned voffA[2], voffB[2];
; #pragma unroll
;     for (int i = 0; i < 2; ++i) { int R, C; stage_rc(tid * 16 + i * 8192, R, C); const int Rb = Epi::PERM ? ((R & ~31) + perm32(R & 31)) : R;
;         voffA[i] = (unsigned)(R * K + C) * 2u; voffB[i] = (unsigned)(Rb * K + C) * 2u; }
;     const size_t kstep = (size_t)(BK * 2);
;     const size_t hstep = (size_t)HALF * K * 2;
;     const size_t tstep = 2 * hstep;
;     const unsigned ldsw = (unsigned)wid * 1024u;
;     const int aoff = lds_byte(wr * 64 + fr, fq * 8), boff = lds_byte(wc * 32 + fr, fq * 8);
;     ...
;     Unit cur, nxt; int ui = 0;
;     if (!S.next(0, cur)) return;
;     f32x4 acc[2][2][4][2];
; #pragma unroll
;     for (int a = 0; a < 2; ++a)
; #pragma unroll
;         for (int b = 0; b < 2; ++b)
; #pragma unroll
;             for (int m = 0; m < 4; ++m)
; #pragma unroll
;                 for (int n = 0; n < 2; ++n) acc[a][b][m][n] = (f32x4){0.f, 0.f, 0.f, 0.f};
;     bf16x8 At[4][2], B0[2][2], B1[2][2];
;     const char* cA = (const char*)g.A + (size_t)cur.pm * tstep; const char* cB = (const char*)g.Bt + (size_t)cur.pn * tstep;
;     PG8_STAGE(PG8_SB(0, 0), cB, voffB); PG8_STAGE(PG8_SA(0, 0), cA, voffA); PG8_STAGE(PG8_SB(0, 1), cB + hstep, voffB); PG8_STAGE(PG8_SA(0, 1), cA + hstep, voffA);
;     if (wr == 1) PG8_BAR;
; DEV void run_phase(const P& p, int ph, LAS unsigned char* lds) {
;     ...
;     case L0_GU1: case L1_GU1: case L0_GU2: case L1_GU2: {
;         const int second = (ph == L0_GU2 || ph == L1_GU2) ? 1 : 0; const int k = 2 * L + second; EpiSwiglu E{ACT, SS + (size_t)(4 * L + (second ? 3 : 0)) * 65536};
;         run_gemm(lds, XB, (const u16*)(ws + O_WGU + k * SZ_WGU), 8192, 11264, 2048, E, bx);
;         idle_conv(p, (ph == L0_GU1) ? 1 : (ph == L0_GU2) ? 4 : (ph == L1_GU1) ? 5 : 8, 32 * 44, bx, G);
.LBB0_747:
	s_nop 0
	v_readlane_b32 s0, v254, 30
	v_readlane_b32 s1, v254, 31
	s_and_b64 vcc, exec, s[0:1]
	s_cbranch_vccz .LBB0_784
	v_readlane_b32 s0, v250, 7
	v_readlane_b32 s1, v250, 8
	s_cmp_eq_u32 s0, 12
	v_readlane_b32 s0, v250, 1
	s_mov_b32 s26, s0
	v_mov_b32_e32 v8, v198
	v_readlane_b32 s8, v254, 20
	s_cselect_b64 s[6:7], -1, 0
	s_cmpk_gt_i32 s8, 0x57f
	v_readfirstlane_b32 s27, v8
	v_readlane_b32 s1, v250, 2
	s_cbranch_scc1 .LBB0_760
	v_readlane_b32 s0, v250, 7
	v_readlane_b32 s1, v250, 8
	s_cmp_eq_u32 s0, 22
	s_cselect_b64 s[0:1], -1, 0
	v_readlane_b32 s4, v254, 26
	s_or_b64 s[0:1], s[6:7], s[0:1]
	v_readlane_b32 s5, v254, 27
	v_cndmask_b32_e64 v0, 0, 1, s[0:1]
	s_and_b64 s[4:5], s[4:5], exec
	v_readfirstlane_b32 s5, v0
	v_lshlrev_b32_e32 v0, 4, v8
	s_waitcnt lgkmcnt(0)
	v_add_u32_e32 v1, 0x2000, v0
	v_ashrrev_i32_e32 v2, 31, v1
	v_lshrrev_b32_e32 v2, 22, v2
	v_add_u32_e32 v2, v1, v2
	v_ashrrev_i32_e32 v9, 10, v2
	v_mul_i32_i24_e32 v2, 0x400, v9
	v_sub_u32_e32 v1, v1, v2
	v_lshrrev_b32_e32 v2, 4, v1
	v_bitop3_b32 v1, v2, v1, 32 bitop3:0x6c
	v_ashrrev_i32_e32 v2, 31, v1
	v_lshrrev_b32_e32 v2, 26, v2
	s_cselect_b32 s4, 2, 0
	v_add_u32_e32 v2, v1, v2
	v_lshlrev_b32_e32 v3, 3, v9
	s_or_b32 s4, s4, s5
	v_ashrrev_i32_e32 v10, 6, v2
	v_and_b32_e32 v3, -16, v3
	s_mul_i32 s4, s4, 0x2c00000
	v_add_u32_e32 v3, v10, v3
	s_add_u32 s28, s90, s4
	v_and_b32_e32 v4, 3, v10
	s_mov_b32 s4, 0xfffe0
	v_lshrrev_b32_e32 v5, 2, v3
	v_lshlrev_b32_e32 v6, 1, v3
	v_and_b32_e32 v2, 0xc0, v2
	v_and_or_b32 v4, v3, s4, v4
	v_and_b32_e32 v5, 4, v5
	v_and_b32_e32 v6, 24, v6
	v_sub_u32_e32 v1, v1, v2
	v_or3_b32 v4, v4, v5, v6
	v_lshlrev_b32_e32 v5, 5, v9
	v_ashrrev_i16_sdwa v1, v203, sext(v1) dst_sel:DWORD dst_unused:UNUSED_PAD src0_sel:DWORD src1_sel:BYTE_0
	v_and_b32_e32 v5, 32, v5
	v_bfe_i32 v11, v1, 0, 16
	v_add_lshl_u32 v1, v5, v11, 1
	v_lshl_add_u32 v136, v4, 12, v1
	v_lshl_add_u32 v138, v3, 12, v1
	v_bfe_i32 v1, v8, 27, 1
	v_lshrrev_b32_e32 v1, 22, v1
	v_add_u32_e32 v1, v0, v1
	v_and_b32_e32 v1, 0xfffffc00, v1
	v_sub_u32_e32 v0, v0, v1
	v_lshrrev_b32_e32 v1, 4, v0
	v_bitop3_b32 v1, v1, v0, 32 bitop3:0x6c
	v_ashrrev_i32_e32 v0, 31, v0
	v_lshrrev_b32_e32 v0, 26, v0
	v_add_u32_e32 v0, v1, v0
	v_ashrrev_i32_e32 v12, 6, v0
	v_ashrrev_i32_e32 v0, 31, v8
	v_lshrrev_b32_e32 v0, 26, v0
	v_add_u32_e32 v0, v8, v0
	v_ashrrev_i32_e32 v13, 6, v0
	v_lshlrev_b32_e32 v0, 3, v13
	v_and_b32_e32 v0, -16, v0
	s_addc_u32 s29, s91, 0
	v_add_u32_e32 v0, v12, v0
	v_and_b32_e32 v2, 3, v12
	s_ashr_i32 s31, s8, 31
	v_and_or_b32 v2, v0, s4, v2
	s_lshr_b32 s4, s31, 29
	s_add_i32 s4, s8, s4
	s_ashr_i32 s14, s27, 6
	s_ashr_i32 s5, s4, 3
	s_and_b32 s4, s4, -8
	s_ashr_i32 s11, s27, 8
	s_lshl_b32 s30, s14, 10
	s_sub_i32 s4, s8, s4
	s_cmp_lt_i32 s4, 0
	s_movk_i32 s8, 0xb1
	s_cselect_b32 s8, s8, 0xb0
	s_mul_i32 s4, s8, s4
	s_add_i32 s4, s4, s5
	s_mul_hi_i32 s5, s4, 0x2e8ba2e9
	s_lshr_b32 s8, s5, 31
	s_ashr_i32 s5, s5, 6
	s_add_i32 s5, s5, s8
	s_lshl_b32 s8, s5, 3
	s_mulk_i32 s5, 0x160
	s_sub_i32 s4, s4, s5
	s_sext_i32_i16 s5, s4
	s_bfe_u32 s5, s5, 0x3001c
	s_add_i32 s5, s4, s5
	s_sext_i32_i16 s9, s5
	s_and_b32 s5, s5, 0xfff8
	v_lshrrev_b32_e32 v3, 2, v0
	v_lshlrev_b32_e32 v4, 1, v0
	s_sub_i32 s4, s4, s5
	v_and_b32_e32 v3, 4, v3
	v_and_b32_e32 v4, 24, v4
	s_sext_i32_i16 s4, s4
	v_or3_b32 v2, v2, v3, v4
	v_mul_i32_i24_e32 v4, 64, v12
	s_lshr_b32 s10, s9, 3
	s_add_i32 s4, s8, s4
	v_sub_u32_e32 v1, v1, v4
	s_ashr_i32 s5, s4, 31
	s_bfe_i64 s[16:17], s[10:11], 0x100000
	v_lshlrev_b32_e32 v3, 5, v13
	v_ashrrev_i16_sdwa v1, v203, sext(v1) dst_sel:DWORD dst_unused:UNUSED_PAD src0_sel:DWORD src1_sel:BYTE_0
	s_lshl_b64 s[8:9], s[4:5], 20
	s_lshl_b64 s[16:17], s[16:17], 20
	v_and_b32_e32 v3, 32, v3
	v_bfe_i32 v14, v1, 0, 16
	s_add_u32 s22, s28, s16
	v_add_lshl_u32 v1, v3, v14, 1
	s_addc_u32 s23, s29, s17
	s_add_i32 s34, s30, 0
	v_lshl_add_u32 v160, v2, 12, v1
	s_add_i32 m0, s34, 0x10000
	v_readlane_b32 s16, v250, 9
	global_load_lds_dwordx4 v160, s[22:23]
	s_add_i32 m0, s34, 0x12000
	v_readlane_b32 s17, v250, 10
	s_add_u32 s20, s16, s8
	v_lshl_add_u32 v140, v0, 12, v1
	global_load_lds_dwordx4 v136, s[22:23]
	s_addc_u32 s21, s17, s9
	s_mov_b32 m0, s34
	s_add_i32 s35, s34, 0x2000
	global_load_lds_dwordx4 v140, s[20:21]
	s_mov_b32 m0, s35
	s_add_u32 s8, s22, 0x80000
	global_load_lds_dwordx4 v138, s[20:21]
	s_addc_u32 s9, s23, 0
	s_add_i32 m0, s34, 0x14000
	v_mov_b32_e32 v137, v161
	global_load_lds_dwordx4 v160, s[8:9]
	s_add_i32 m0, s34, 0x16000
	v_mov_b32_e32 v141, v161
	global_load_lds_dwordx4 v136, s[8:9]
	s_add_u32 s8, s20, 0x80000
	s_addc_u32 s9, s21, 0
	s_add_i32 s36, s34, 0x4000
	s_mov_b32 m0, s36
	s_add_i32 s37, s34, 0x6000
	global_load_lds_dwordx4 v140, s[8:9]
	s_mov_b32 m0, s37
	v_mov_b32_e32 v139, v161
	global_load_lds_dwordx4 v138, s[8:9]
	v_lshl_add_u64 v[6:7], s[22:23], 0, v[160:161]
	v_lshl_add_u64 v[4:5], s[22:23], 0, v[136:137]
	v_lshl_add_u64 v[2:3], s[20:21], 0, v[140:141]
	s_cmp_lg_u32 s11, 1
	v_lshl_add_u64 v[0:1], s[20:21], 0, v[138:139]
	s_setprio 1
	s_cbranch_scc1 .LBB0_751
	s_barrier
	s_setprio 0
